# speedup vs baseline: 1.0043x; 1.0043x over previous
; __device__ __forceinline__ void store_inproj(float* st, KP p, int grow0, int bcol, int tix) {
;     ...
;   for (int it = tix; it < 256 * 16; it += NTHREADS) {
;     const int col = it >> 4, rc = it & 15;
;     const int gcol = bcol + col;
;     const int grp = gcol >> 9;
;     int tbase;
;     switch (grp) { case 2: tbase = 0; break; case 5: tbase = 512; break; case 8: tbase = 1024; break; case 9: tbase = 1536; break; default: tbase = -1; break; }
;     if (tbase < 0) continue;
;     float v[8];
; #pragma unroll
;     for (int j = 0; j < 8; ++j) v[j] = st[(rc * 8 + j) * STS + col];
;     const int tcol = tbase + (gcol & 511);
;     *(uint4*)(Tb + ((size_t)tcol * 2 + b) * LP + pos0 + rc * 8) = pack8u(v);
.LBB0_477:
	s_or_b64 exec, exec, s[28:29]
	v_lshrrev_b32_e32 v0, 1, v133
	v_and_b32_e32 v183, 0xf0, v0
	v_and_b32_e32 v0, 8, v0
	v_and_or_b32 v183, v133, 15, v183
	v_mul_u32_u24_e32 v68, 0x410, v0
	v_lshlrev_b32_e32 v0, 1, v0
	v_lshl_add_u64 v[66:67], s[12:13], 0, v[0:1]
	v_add_u32_e32 v70, 0, v68
	s_waitcnt lgkmcnt(0)
	s_barrier
	s_and_saveexec_b64 s[6:7], s[4:5]
	s_cbranch_execz .LBB0_498
	s_ashr_i32 s27, s26, 31
	v_lshl_add_u64 v[68:69], s[26:27], 1, v[66:67]
	s_mov_b64 s[8:9], 0
	v_mov_b32_e32 v0, v133
	s_branch .LBB0_480
.LBB0_479:
	s_or_b64 exec, exec, s[26:27]
	v_add_u32_e32 v70, 0x4100, v70
	v_lshl_add_u64 v[68:69], v[68:69], 0, 32
	v_add_u32_e32 v71, 0x200, v0
	v_cmp_lt_i32_e32 vcc, s61, v0
	s_or_b64 s[8:9], vcc, s[8:9]
	v_mov_b32_e32 v0, v71
	s_andn2_b64 exec, exec, s[8:9]
	s_cbranch_execz .LBB0_498
.LBB0_480:
	v_mov_b32_e32 v72, v183
	v_add_u32_e32 v71, s14, v72
	v_ashrrev_i32_e32 v74, 9, v71
	v_cmp_lt_i32_e32 vcc, 7, v74
	s_mov_b64 s[24:25], 0
	s_and_saveexec_b64 s[26:27], vcc
	s_xor_b64 s[26:27], exec, s[26:27]
	s_cbranch_execnz .LBB0_483
	s_andn2_saveexec_b64 s[26:27], s[26:27]
	s_cbranch_execnz .LBB0_490

; __device__ __forceinline__ void store_inproj(float* st, KP p, int grow0, int bcol, int tix) {
;     ...
;   for (int it = tix; it < 256 * 16; it += NTHREADS) {
;     const int col = it >> 4, rc = it & 15;
;     const int gcol = bcol + col;
;     const int grp = gcol >> 9;
;     int tbase;
;     switch (grp) { case 2: tbase = 0; break; case 5: tbase = 512; break; case 8: tbase = 1024; break; case 9: tbase = 1536; break; default: tbase = -1; break; }
;     if (tbase < 0) continue;
;     float v[8];
; #pragma unroll
;     for (int j = 0; j < 8; ++j) v[j] = st[(rc * 8 + j) * STS + col];
;     const int tcol = tbase + (gcol & 511);
;     *(uint4*)(Tb + ((size_t)tcol * 2 + b) * LP + pos0 + rc * 8) = pack8u(v);
.LBB0_554:
	s_or_b64 exec, exec, s[26:27]
	s_waitcnt lgkmcnt(0)
	s_barrier
	s_and_saveexec_b64 s[6:7], s[4:5]
	s_cbranch_execz .LBB0_410
	s_ashr_i32 s25, s24, 31
	v_lshl_add_u64 v[2:3], s[24:25], 1, v[66:67]
	v_lshrrev_b32_e32 v0, 1, v133
	v_and_b32_e32 v0, 8, v0
	v_mul_u32_u24_e32 v70, 0x410, v0
	s_mov_b64 s[4:5], 0
	s_branch .LBB0_557
.LBB0_556:
	s_or_b64 exec, exec, s[16:17]
	v_add_u32_e32 v70, 0x4100, v70
	v_lshl_add_u64 v[2:3], v[2:3], 0, 32
	v_add_u32_e32 v0, 0x200, v133
	v_cmp_lt_i32_e32 vcc, s61, v133
	s_or_b64 s[4:5], vcc, s[4:5]
	v_mov_b32_e32 v133, v0
	s_andn2_b64 exec, exec, s[4:5]
	s_cbranch_execz .LBB0_410
.LBB0_557:
	v_mov_b32_e32 v4, v183
	v_add_u32_e32 v0, s14, v4
	v_ashrrev_i32_e32 v6, 9, v0
	v_cmp_lt_i32_e32 vcc, 7, v6
	s_mov_b64 s[8:9], 0
	s_and_saveexec_b64 s[16:17], vcc
	s_xor_b64 s[16:17], exec, s[16:17]
	s_cbranch_execnz .LBB0_560
	s_andn2_saveexec_b64 s[16:17], s[16:17]
	s_cbranch_execnz .LBB0_567
